# w_up int8 transpose: column-step load and its division overlapped with the 16 row loads (counted vmcnt) instead of load+vmcnt(0)+divide before them; plus pp schedule rebalance
# speedup vs baseline: 1.0317x; 1.0063x over previous
; __device__ __forceinline__ void ph_transpose_q8(const TrJob job, LAS unsigned* scr, int gw, int NGW, int lane) {
;     ...
;     for (int item = gw; item < nitems; item += NGW) {
;         const int kb = item / ngrp, gq = item % ngrp, k0 = 64 * kb, r0 = 64 * gq, sb = srcbase_of(job.kind, r0);
;         const int n4 = (lane & 15) * 4; const bool inb = sb + n4 < job.N;
;         f32x4 isc = {0.f, 0.f, 0.f, 0.f};
;         if (inb) { const f32x4 cm = *(const f32x4*)(job.qmax + sb + n4);
; #pragma unroll
;             for (int e = 0; e < 4; ++e) isc[e] = cm[e] > 0.f ? 127.f / cm[e] : 0.f; }
;         f32x4 v[4][4];
; #pragma unroll
;         for (int i = 0; i < 4; ++i) { const int kq = 4 * i + (lane >> 4);
; #pragma unroll
;             for (int q = 0; q < 4; ++q) { const int k = k0 + 4 * kq + q; f32x4 t = {0.f, 0.f, 0.f, 0.f};
;                 if (inb) t = *(const f32x4*)(W + (size_t)k * job.N + sb + n4);
;                 v[i][q] = t; } }
.LBB0_842:
	s_mul_hi_i32 s1, s43, 0x2fa0be83
	s_lshr_b32 s6, s1, 31
	s_ashr_i32 s1, s1, 6
	s_add_i32 s1, s1, s6
	s_mul_i32 s6, s1, 0xffffaa00
	s_mul_i32 s7, s1, 0xffffd500
	s_add_i32 s45, s4, s6
	s_bfe_i32 s6, s43, 0x10001
	s_add_i32 s7, s36, s7
	s_and_b32 s6, s6, 0x2b00
	s_and_b32 s44, s7, 0xffffff80
	s_add_i32 s6, s6, s44
	s_and_b32 s7, s45, 64
	s_or_b32 s26, s6, s7
	v_cmp_lt_i32_e64 s[6:7], s26, v93
	v_cmp_ge_i32_e32 vcc, s26, v93
	s_and_saveexec_b64 s[8:9], vcc
	s_xor_b64 s[8:9], exec, s[8:9]
	s_or_saveexec_b64 s[28:29], s[8:9]
	v_mov_b32_e32 v2, 0
	v_mov_b64_e32 v[4:5], s[26:27]
	v_mov_b32_e32 v72, 0
	v_mov_b32_e32 v73, 0
	v_mov_b32_e32 v74, 0
	v_mov_b32_e32 v75, 0
	s_xor_b64 exec, exec, s[28:29]
	s_cbranch_execz .LBB0_844
	s_ashr_i32 s31, s26, 31
	s_mov_b32 s30, s26
	v_lshl_add_u64 v[4:5], s[30:31], 2, v[66:67]
	global_load_dwordx4 v[120:123], v[4:5], off
	v_mov_b64_e32 v[4:5], s[30:31]

; __device__ __forceinline__ void ph_transpose_q8(const TrJob job, LAS unsigned* scr, int gw, int NGW, int lane) {
;     ...
;         if (inb) { const f32x4 cm = *(const f32x4*)(job.qmax + sb + n4);
; #pragma unroll
;             for (int e = 0; e < 4; ++e) isc[e] = cm[e] > 0.f ? 127.f / cm[e] : 0.f; }
;         f32x4 v[4][4];
; #pragma unroll
;         for (int i = 0; i < 4; ++i) { const int kq = 4 * i + (lane >> 4);
; #pragma unroll
;             for (int q = 0; q < 4; ++q) { const int k = k0 + 4 * kq + q; f32x4 t = {0.f, 0.f, 0.f, 0.f};
;                 if (inb) t = *(const f32x4*)(W + (size_t)k * job.N + sb + n4);
;                 v[i][q] = t; } }
;         asm volatile("" ::: "memory");
;         { float kv[4][4];
; #pragma unroll
;           for (int i = 0; i < 4; ++i) { const int kq = 4 * i + (lane >> 4);
; #pragma unroll
;               for (int q = 0; q < 4; ++q) { const int k = k0 + 4 * kq + q; kv[i][q] = (ks && k < job.kscale_n) ? ks[k] : 1.f; } }
.LBB0_876:
	s_or_b64 exec, exec, s[10:11]
	v_cmp_lt_i32_e64 s[54:55], s26, v93
	s_and_saveexec_b64 s[56:57], s[54:55]
	s_cbranch_execz .Lq8u_div_done
	s_waitcnt vmcnt(16)
	v_div_scale_f32 v124, s[58:59], v120, v120, s39
	v_div_scale_f32 v126, s[58:59], v121, v121, s39
	v_rcp_f32_e32 v132, v124
	v_rcp_f32_e32 v133, v126
	v_div_scale_f32 v128, s[60:61], v122, v122, s39
	v_rcp_f32_e32 v134, v128
	v_div_scale_f32 v130, s[62:63], v123, v123, s39
	v_fma_f32 v136, -v124, v132, 1.0
	v_div_scale_f32 v125, vcc, s39, v120, s39
	v_rcp_f32_e32 v135, v130
	v_fma_f32 v137, -v126, v133, 1.0
	v_fmac_f32_e32 v132, v136, v132
	v_div_scale_f32 v127, s[58:59], s39, v121, s39
	v_fmac_f32_e32 v133, v137, v133
	v_mul_f32_e32 v136, v125, v132
	v_fma_f32 v138, -v128, v134, 1.0
	v_mul_f32_e32 v137, v127, v133
	v_fma_f32 v140, -v124, v136, v125
	v_div_scale_f32 v129, s[60:61], s39, v122, s39
	v_fmac_f32_e32 v134, v138, v134
	v_fma_f32 v141, -v126, v137, v127
	v_fmac_f32_e32 v136, v140, v132
	v_fma_f32 v139, -v130, v135, 1.0
	v_mul_f32_e32 v138, v129, v134
	v_fmac_f32_e32 v137, v141, v133
	v_fma_f32 v124, -v124, v136, v125
	v_div_scale_f32 v131, s[62:63], s39, v123, s39
	v_fmac_f32_e32 v135, v139, v135
	v_fma_f32 v142, -v128, v138, v129
	v_fma_f32 v125, -v126, v137, v127
	v_div_fmas_f32 v124, v124, v132, v136
	s_mov_b64 vcc, s[58:59]
	v_mul_f32_e32 v139, v131, v135
	v_fmac_f32_e32 v138, v142, v134
	v_div_fixup_f32 v124, v124, v120, s39
	v_div_fmas_f32 v125, v125, v133, v137
	v_cmp_lt_f32_e32 vcc, 0, v120
	v_fma_f32 v143, -v130, v139, v131
	v_fma_f32 v126, -v128, v138, v129
	v_cndmask_b32_e32 v72, 0, v124, vcc
	s_mov_b64 vcc, s[60:61]
	v_fmac_f32_e32 v139, v143, v135
	v_div_fixup_f32 v124, v125, v121, s39
	v_div_fmas_f32 v120, v126, v134, v138
	v_cmp_lt_f32_e32 vcc, 0, v121
	v_fma_f32 v127, -v130, v139, v131
	s_nop 0
	v_cndmask_b32_e32 v73, 0, v124, vcc
	s_mov_b64 vcc, s[62:63]
	v_div_fixup_f32 v124, v120, v122, s39
	v_div_fmas_f32 v120, v127, v135, v139
	v_cmp_lt_f32_e32 vcc, 0, v122
	s_nop 1
	v_cndmask_b32_e32 v74, 0, v124, vcc
	v_div_fixup_f32 v124, v120, v123, s39
	v_cmp_lt_f32_e32 vcc, 0, v123
	s_nop 1
	v_cndmask_b32_e32 v75, 0, v124, vcc
.Lq8u_div_done:
	s_or_b64 exec, exec, s[56:57]
	v_cmp_gt_i32_e32 vcc, s41, v76
	s_and_b64 s[10:11], s[18:19], vcc
	v_mov_b32_e32 v78, 1.0
	v_ashrrev_i32_e32 v77, 31, v76
	v_mov_b32_e32 v80, 1.0
	s_and_saveexec_b64 s[6:7], s[10:11]
	s_cbranch_execz .LBB0_878
	v_lshl_add_u64 v[108:109], v[76:77], 2, s[16:17]
	global_load_dword v80, v[108:109], off
